# static priority raise (s_setprio 2) for waves 4-7 during the PEER expert sweeps
# speedup vs baseline: 1.0099x; 1.0054x over previous
; __device__ __forceinline__ float key2f(unsigned k) { return __uint_as_float((k & 0x80000000u) ? (k & 0x7fffffffu) : ~k); }
; __device__ void ph_peer(const float* __restrict__ SC, const bf16_t* __restrict__ H  , const float* __restrict__ gffn, const unsigned char* __restrict__ U, const unsigned char* __restrict__ V, float* X, const float* __restrict__ fgain) {
;     ...
; #pragma unroll
;             for (int u = 0; u < 2; ++u) {
;                 const float bs = key2f(best[u] & ~255u);
;                 const int pos = 255 - (int)(best[u] & 255u);
;                 const int e0 = __shfl(n0[u], (pos >> 4) & 15), e1 = __shfl(n1[u], pos & 15);
;                 const float mxs = __shfl(bs, 0);
;                 float e = lane < 16 ? __expf((bs - mxs) * rstd) : 0.f;
;                 const float den = row16_sum(e);
;                 const int iv = __shfl(e0 * 128 + e1, lane & 15); const float gv = __shfl(e / den, lane & 15);
;                 const int hh = h + u;
;                 if (grp == (hh & 3)) { if (hh < 4) { idx_lo = iv; g_lo = gv; } else { idx_hi = iv; g_hi = gv; } } }
.Lpeer_partB_b:
	v_lshrrev_b32_e32 v2, 11, v72
	v_lshrrev_b32_e32 v3, 6, v131
	v_lshl_add_u32 v2, v2, 3, v91
	v_mul_u32_u24_e32 v3, 0x1c00, v3
	v_mul_u32_u24_e32 v2, 0x70, v2
	v_and_b32_e32 v4, 15, v74
	v_add_u32_e32 v3, 0x12000, v3
	v_add_u32_e32 v2, v3, v2
	v_add_u32_e32 v5, v2, v4
	v_lshl_add_u32 v6, v4, 2, v2
	ds_read_u8 v7, v5 offset:96
	ds_read_u8 v8, v5 offset:544
	ds_read_b32 v9, v6 offset:32
	ds_read_b32 v10, v6 offset:480
	ds_read_b32 v11, v2 offset:32
	ds_read_b32 v13, v2 offset:480
	s_waitcnt lgkmcnt(4)
	v_not_b32_e32 v7, v7
	v_not_b32_e32 v8, v8
	v_bfe_u32 v14, v7, 4, 4
	v_and_b32_e32 v7, 15, v7
	v_bfe_u32 v15, v8, 4, 4
	v_and_b32_e32 v8, 15, v8
	v_add_u32_e32 v14, v2, v14
	v_add_u32_e32 v7, v2, v7
	v_add_u32_e32 v15, v2, v15
	v_add_u32_e32 v8, v2, v8
	ds_read_u8 v14, v14
	ds_read_u8 v7, v7 offset:16
	ds_read_u8 v15, v15 offset:448
	ds_read_u8 v8, v8 offset:464
	s_waitcnt lgkmcnt(4)
	v_sub_f32_e32 v9, v9, v11
	v_sub_f32_e32 v10, v10, v13
	v_mul_f32_e32 v9, v12, v9
	v_mul_f32_e32 v10, v12, v10
	v_mul_f32_e32 v9, 0x3fb8aa3b, v9
	v_mul_f32_e32 v10, 0x3fb8aa3b, v10
	v_exp_f32_e32 v9, v9
	v_exp_f32_e32 v10, v10
	s_nop 1
	v_add_f32_dpp v11, v9, v9 quad_perm:[1,0,3,2] row_mask:0xf bank_mask:0xf bound_ctrl:1
	v_add_f32_dpp v13, v10, v10 quad_perm:[1,0,3,2] row_mask:0xf bank_mask:0xf bound_ctrl:1
	s_nop 0
	v_add_f32_dpp v11, v11, v11 quad_perm:[2,3,0,1] row_mask:0xf bank_mask:0xf bound_ctrl:1
	v_add_f32_dpp v13, v13, v13 quad_perm:[2,3,0,1] row_mask:0xf bank_mask:0xf bound_ctrl:1
	s_nop 0
	v_add_f32_dpp v11, v11, v11 row_half_mirror row_mask:0xf bank_mask:0xf bound_ctrl:1
	v_add_f32_dpp v13, v13, v13 row_half_mirror row_mask:0xf bank_mask:0xf bound_ctrl:1
	s_nop 0
	v_add_f32_dpp v11, v11, v11 row_mirror row_mask:0xf bank_mask:0xf bound_ctrl:1
	v_add_f32_dpp v13, v13, v13 row_mirror row_mask:0xf bank_mask:0xf bound_ctrl:1
	s_nop 0
	v_div_scale_f32 v16, s[0:1], v11, v11, v9
	v_div_scale_f32 v17, s[0:1], v13, v13, v10
	v_rcp_f32_e32 v18, v16
	v_rcp_f32_e32 v19, v17
	s_nop 0
	v_fma_f32 v20, -v16, v18, 1.0
	v_fma_f32 v21, -v17, v19, 1.0
	v_fmac_f32_e32 v18, v20, v18
	v_fmac_f32_e32 v19, v21, v19
	v_div_scale_f32 v20, vcc, v9, v11, v9
	v_mul_f32_e32 v22, v20, v18
	v_fma_f32 v24, -v16, v22, v20
	v_fmac_f32_e32 v22, v24, v18
	v_fma_f32 v20, -v16, v22, v20
	v_div_fmas_f32 v20, v20, v18, v22
	v_div_fixup_f32 v73, v20, v11, v9
	v_div_scale_f32 v21, vcc, v10, v13, v10
	v_mul_f32_e32 v23, v21, v19
	v_fma_f32 v25, -v17, v23, v21
	v_fmac_f32_e32 v23, v25, v19
	v_fma_f32 v21, -v17, v23, v21
	v_div_fmas_f32 v21, v21, v19, v23
	v_div_fixup_f32 v158, v21, v13, v10
	s_waitcnt lgkmcnt(0)
	v_and_b32_e32 v14, 0x7f, v14
	v_and_b32_e32 v7, 0x7f, v7
	v_and_b32_e32 v15, 0x7f, v15
	v_and_b32_e32 v8, 0x7f, v8
	v_lshl_or_b32 v14, v14, 7, v7
	v_lshl_or_b32 v15, v15, 7, v8
	v_xor_b32_e32 v156, 0x3fff, v14
	v_xor_b32_e32 v157, 0x3fff, v15
	v_lshrrev_b32_e32 v2, 11, v156
	v_lshrrev_b32_e32 v3, 11, v157
	s_mov_b32 s2, 0
	v_mov_b32_e32 v6, 0
	v_mov_b32_e32 v7, 0
	v_cmp_eq_u32_e64 s[0:1], 0, v2
	v_cmp_eq_u32_e64 s[6:7], 0, v3
	s_nop 1
	v_mbcnt_lo_u32_b32 v4, s0, 0
	v_mbcnt_lo_u32_b32 v5, s6, 0
	v_mbcnt_hi_u32_b32 v4, s1, v4
	v_mbcnt_hi_u32_b32 v5, s7, v5
	s_bcnt1_i32_b64 s14, s[0:1]
	s_bcnt1_i32_b64 s15, s[6:7]
	v_add_u32_e32 v4, s2, v4
	s_add_i32 s14, s2, s14
	s_nop 0
	v_add_u32_e32 v5, s14, v5
	s_add_i32 s2, s14, s15
	v_cndmask_b32_e64 v6, v6, v4, s[0:1]
	v_cndmask_b32_e64 v7, v7, v5, s[6:7]
	v_cmp_eq_u32_e64 s[0:1], 1, v2
	v_cmp_eq_u32_e64 s[6:7], 1, v3
	s_nop 1
	v_mbcnt_lo_u32_b32 v4, s0, 0
	v_mbcnt_lo_u32_b32 v5, s6, 0
	v_mbcnt_hi_u32_b32 v4, s1, v4
	v_mbcnt_hi_u32_b32 v5, s7, v5
	s_bcnt1_i32_b64 s14, s[0:1]
	s_bcnt1_i32_b64 s15, s[6:7]
	v_add_u32_e32 v4, s2, v4
	s_add_i32 s14, s2, s14
	s_nop 0
	v_add_u32_e32 v5, s14, v5
	s_add_i32 s2, s14, s15
	v_cndmask_b32_e64 v6, v6, v4, s[0:1]
	v_cndmask_b32_e64 v7, v7, v5, s[6:7]
	v_cmp_eq_u32_e64 s[0:1], 2, v2
	v_cmp_eq_u32_e64 s[6:7], 2, v3
	s_nop 1
	v_mbcnt_lo_u32_b32 v4, s0, 0
	v_mbcnt_lo_u32_b32 v5, s6, 0
	v_mbcnt_hi_u32_b32 v4, s1, v4
	v_mbcnt_hi_u32_b32 v5, s7, v5
	s_bcnt1_i32_b64 s14, s[0:1]
	s_bcnt1_i32_b64 s15, s[6:7]
	v_add_u32_e32 v4, s2, v4
	s_add_i32 s14, s2, s14
	s_nop 0
	v_add_u32_e32 v5, s14, v5
	s_add_i32 s2, s14, s15
	v_cndmask_b32_e64 v6, v6, v4, s[0:1]
	v_cndmask_b32_e64 v7, v7, v5, s[6:7]
	v_cmp_eq_u32_e64 s[0:1], 3, v2
	v_cmp_eq_u32_e64 s[6:7], 3, v3
	s_nop 1
	v_mbcnt_lo_u32_b32 v4, s0, 0
	v_mbcnt_lo_u32_b32 v5, s6, 0
	v_mbcnt_hi_u32_b32 v4, s1, v4
	v_mbcnt_hi_u32_b32 v5, s7, v5
	s_bcnt1_i32_b64 s14, s[0:1]
	s_bcnt1_i32_b64 s15, s[6:7]
	v_add_u32_e32 v4, s2, v4
	s_add_i32 s14, s2, s14
	s_nop 0
	v_add_u32_e32 v5, s14, v5
	s_add_i32 s2, s14, s15
	v_cndmask_b32_e64 v6, v6, v4, s[0:1]
	v_cndmask_b32_e64 v7, v7, v5, s[6:7]
	v_cmp_eq_u32_e64 s[0:1], 4, v2
	v_cmp_eq_u32_e64 s[6:7], 4, v3
	s_nop 1
	v_mbcnt_lo_u32_b32 v4, s0, 0
	v_mbcnt_lo_u32_b32 v5, s6, 0
	v_mbcnt_hi_u32_b32 v4, s1, v4
	v_mbcnt_hi_u32_b32 v5, s7, v5
	s_bcnt1_i32_b64 s14, s[0:1]
	s_bcnt1_i32_b64 s15, s[6:7]
	v_add_u32_e32 v4, s2, v4
	s_add_i32 s14, s2, s14
	s_nop 0
	v_add_u32_e32 v5, s14, v5
	s_add_i32 s2, s14, s15
	v_cndmask_b32_e64 v6, v6, v4, s[0:1]
	v_cndmask_b32_e64 v7, v7, v5, s[6:7]
	v_cmp_eq_u32_e64 s[0:1], 5, v2
	v_cmp_eq_u32_e64 s[6:7], 5, v3
	s_nop 1
	v_mbcnt_lo_u32_b32 v4, s0, 0
	v_mbcnt_lo_u32_b32 v5, s6, 0
	v_mbcnt_hi_u32_b32 v4, s1, v4
	v_mbcnt_hi_u32_b32 v5, s7, v5
	s_bcnt1_i32_b64 s14, s[0:1]
	s_bcnt1_i32_b64 s15, s[6:7]
	v_add_u32_e32 v4, s2, v4
	s_add_i32 s14, s2, s14
	s_nop 0
	v_add_u32_e32 v5, s14, v5
	s_add_i32 s2, s14, s15
	v_cndmask_b32_e64 v6, v6, v4, s[0:1]
	v_cndmask_b32_e64 v7, v7, v5, s[6:7]
	v_cmp_eq_u32_e64 s[0:1], 6, v2
	v_cmp_eq_u32_e64 s[6:7], 6, v3
	s_nop 1
	v_mbcnt_lo_u32_b32 v4, s0, 0
	v_mbcnt_lo_u32_b32 v5, s6, 0
	v_mbcnt_hi_u32_b32 v4, s1, v4
	v_mbcnt_hi_u32_b32 v5, s7, v5
	s_bcnt1_i32_b64 s14, s[0:1]
	s_bcnt1_i32_b64 s15, s[6:7]
	v_add_u32_e32 v4, s2, v4
	s_add_i32 s14, s2, s14
	s_nop 0
	v_add_u32_e32 v5, s14, v5
	s_add_i32 s2, s14, s15
	v_cndmask_b32_e64 v6, v6, v4, s[0:1]
	v_cndmask_b32_e64 v7, v7, v5, s[6:7]
	v_cmp_eq_u32_e64 s[0:1], 7, v2
	v_cmp_eq_u32_e64 s[6:7], 7, v3
	s_nop 1
	v_mbcnt_lo_u32_b32 v4, s0, 0
	v_mbcnt_lo_u32_b32 v5, s6, 0
	v_mbcnt_hi_u32_b32 v4, s1, v4
	v_mbcnt_hi_u32_b32 v5, s7, v5
	s_bcnt1_i32_b64 s14, s[0:1]
	s_bcnt1_i32_b64 s15, s[6:7]
	v_add_u32_e32 v4, s2, v4
	s_add_i32 s14, s2, s14
	s_nop 0
	v_add_u32_e32 v5, s14, v5
	s_add_i32 s2, s14, s15
	v_cndmask_b32_e64 v6, v6, v4, s[0:1]
	v_cndmask_b32_e64 v7, v7, v5, s[6:7]
	v_lshrrev_b32_e32 v8, 6, v131
	v_mul_u32_u24_e32 v8, 0x2400, v8
	v_lshl_add_u32 v9, v6, 2, v8
	v_lshl_add_u32 v10, v7, 2, v8
	ds_write_b32 v9, v156 offset:1536
	ds_write_b32 v10, v157 offset:1536
	ds_write_b32 v9, v73 offset:2048
	ds_write_b32 v10, v158 offset:2048
	s_waitcnt vmcnt(0) lgkmcnt(0)
; __device__ __forceinline__ unsigned cvt_pk_bf16(float lo, float hi) { unsigned r; asm volatile("v_cvt_pk_bf16_f32 %0, %1, %2" : "=v"(r) : "v"(lo), "v"(hi)); return r; }
; __device__ __forceinline__ float bflo(unsigned w) { return __uint_as_float(w << 16); }
; __device__ __forceinline__ float bfhi(unsigned w) { return __uint_as_float(w & 0xffff0000u); }
; __device__ void ph_peer(const float* __restrict__ SC, const bf16_t* __restrict__ H  , const float* __restrict__ gffn, const unsigned char* __restrict__ U, const unsigned char* __restrict__ V, float* X, const float* __restrict__ fgain) {
;     ...
;         {   const u32x4* hp = (const u32x4*)(H + (size_t)tok * 1024 + 64 * sub);
; #pragma unroll
;             for (int q = 0; q < 8; ++q) { const u32x4 w = hp[q];
;                 const float4 ga = *(const float4*)(gffn + 64 * sub + q * 8), gb = *(const float4*)(gffn + 64 * sub + q * 8 + 4);
;                 hf2[q * 4 + 0] = cvt_pk_bf16(bflo(w.x) * rstd * ga.x, bfhi(w.x) * rstd * ga.y);
;                 hf2[q * 4 + 1] = cvt_pk_bf16(bflo(w.y) * rstd * ga.z, bfhi(w.y) * rstd * ga.w);
;                 hf2[q * 4 + 2] = cvt_pk_bf16(bflo(w.z) * rstd * gb.x, bfhi(w.z) * rstd * gb.y);
;                 hf2[q * 4 + 3] = cvt_pk_bf16(bflo(w.w) * rstd * gb.z, bfhi(w.w) * rstd * gb.w); } }
;         const int half = lane >> 5, c32 = lane & 31;
;         float acc[32];
; #pragma unroll
;         for (int i = 0; i < 32; ++i) acc[i] = 0.f;
;         __builtin_amdgcn_s_setprio(1);
	v_lshlrev_b32_e32 v2, 16, v218
	v_and_b32_e32 v3, 0xffff0000, v218
	v_lshlrev_b32_e32 v4, 16, v219
	v_and_b32_e32 v5, 0xffff0000, v219
	v_pk_mul_f32 v[2:3], v[2:3], v[12:13] op_sel_hi:[1,0]
	v_pk_mul_f32 v[4:5], v[4:5], v[12:13] op_sel_hi:[1,0]
	v_pk_mul_f32 v[2:3], v[2:3], v[64:65]
	v_pk_mul_f32 v[4:5], v[4:5], v[66:67]
	v_cvt_pk_bf16_f32 v212, v2, v3
	v_cvt_pk_bf16_f32 v213, v4, v5
	v_lshlrev_b32_e32 v2, 16, v220
	v_and_b32_e32 v3, 0xffff0000, v220
	v_lshlrev_b32_e32 v4, 16, v221
	v_and_b32_e32 v5, 0xffff0000, v221
	v_pk_mul_f32 v[2:3], v[2:3], v[12:13] op_sel_hi:[1,0]
	v_pk_mul_f32 v[4:5], v[4:5], v[12:13] op_sel_hi:[1,0]
	v_pk_mul_f32 v[2:3], v[2:3], v[68:69]
	v_pk_mul_f32 v[4:5], v[4:5], v[70:71]
	v_cvt_pk_bf16_f32 v214, v2, v3
	v_cvt_pk_bf16_f32 v215, v4, v5
	v_lshlrev_b32_e32 v2, 16, v222
	v_and_b32_e32 v3, 0xffff0000, v222
	v_lshlrev_b32_e32 v4, 16, v223
	v_and_b32_e32 v5, 0xffff0000, v223
	v_pk_mul_f32 v[2:3], v[2:3], v[12:13] op_sel_hi:[1,0]
	v_pk_mul_f32 v[4:5], v[4:5], v[12:13] op_sel_hi:[1,0]
	v_pk_mul_f32 v[2:3], v[2:3], v[32:33]
	v_pk_mul_f32 v[4:5], v[4:5], v[34:35]
	v_cvt_pk_bf16_f32 v218, v2, v3
	v_cvt_pk_bf16_f32 v219, v4, v5
	v_lshlrev_b32_e32 v2, 16, v224
	v_and_b32_e32 v3, 0xffff0000, v224
	v_lshlrev_b32_e32 v4, 16, v225
	v_and_b32_e32 v5, 0xffff0000, v225
	v_pk_mul_f32 v[2:3], v[2:3], v[12:13] op_sel_hi:[1,0]
	v_pk_mul_f32 v[4:5], v[4:5], v[12:13] op_sel_hi:[1,0]
	v_pk_mul_f32 v[2:3], v[2:3], v[36:37]
	v_pk_mul_f32 v[4:5], v[4:5], v[38:39]
	v_cvt_pk_bf16_f32 v220, v2, v3
	v_cvt_pk_bf16_f32 v221, v4, v5
	v_lshlrev_b32_e32 v2, 16, v226
	v_and_b32_e32 v3, 0xffff0000, v226
	v_lshlrev_b32_e32 v4, 16, v227
	v_and_b32_e32 v5, 0xffff0000, v227
	v_pk_mul_f32 v[2:3], v[2:3], v[12:13] op_sel_hi:[1,0]
	v_pk_mul_f32 v[4:5], v[4:5], v[12:13] op_sel_hi:[1,0]
	v_pk_mul_f32 v[2:3], v[2:3], v[40:41]
	v_pk_mul_f32 v[4:5], v[4:5], v[42:43]
	v_cvt_pk_bf16_f32 v222, v2, v3
	v_cvt_pk_bf16_f32 v223, v4, v5
	v_lshlrev_b32_e32 v2, 16, v228
	v_and_b32_e32 v3, 0xffff0000, v228
	v_lshlrev_b32_e32 v4, 16, v229
	v_and_b32_e32 v5, 0xffff0000, v229
	v_pk_mul_f32 v[2:3], v[2:3], v[12:13] op_sel_hi:[1,0]
	v_pk_mul_f32 v[4:5], v[4:5], v[12:13] op_sel_hi:[1,0]
	v_pk_mul_f32 v[2:3], v[2:3], v[44:45]
	v_pk_mul_f32 v[4:5], v[4:5], v[46:47]
	v_cvt_pk_bf16_f32 v224, v2, v3
	v_cvt_pk_bf16_f32 v225, v4, v5
	v_lshlrev_b32_e32 v2, 16, v230
	v_and_b32_e32 v3, 0xffff0000, v230
	v_lshlrev_b32_e32 v4, 16, v231
	v_and_b32_e32 v5, 0xffff0000, v231
	v_pk_mul_f32 v[2:3], v[2:3], v[12:13] op_sel_hi:[1,0]
	v_pk_mul_f32 v[4:5], v[4:5], v[12:13] op_sel_hi:[1,0]
	v_pk_mul_f32 v[2:3], v[2:3], v[48:49]
	v_pk_mul_f32 v[4:5], v[4:5], v[50:51]
	v_cvt_pk_bf16_f32 v226, v2, v3
	v_cvt_pk_bf16_f32 v227, v4, v5
	v_lshlrev_b32_e32 v2, 16, v232
	v_and_b32_e32 v3, 0xffff0000, v232
	v_lshlrev_b32_e32 v4, 16, v233
	v_and_b32_e32 v5, 0xffff0000, v233
	v_pk_mul_f32 v[2:3], v[2:3], v[12:13] op_sel_hi:[1,0]
	v_pk_mul_f32 v[4:5], v[4:5], v[12:13] op_sel_hi:[1,0]
	v_pk_mul_f32 v[2:3], v[2:3], v[52:53]
	v_pk_mul_f32 v[4:5], v[4:5], v[54:55]
	v_cvt_pk_bf16_f32 v228, v2, v3
	v_cvt_pk_bf16_f32 v229, v4, v5
	v_lshlrev_b32_e32 v2, 16, v234
	v_and_b32_e32 v3, 0xffff0000, v234
	v_lshlrev_b32_e32 v4, 16, v235
	v_and_b32_e32 v5, 0xffff0000, v235
	v_pk_mul_f32 v[2:3], v[2:3], v[12:13] op_sel_hi:[1,0]
	v_pk_mul_f32 v[4:5], v[4:5], v[12:13] op_sel_hi:[1,0]
	v_pk_mul_f32 v[2:3], v[2:3], v[56:57]
	v_pk_mul_f32 v[4:5], v[4:5], v[58:59]
	v_cvt_pk_bf16_f32 v230, v2, v3
	v_cvt_pk_bf16_f32 v231, v4, v5
	v_lshlrev_b32_e32 v2, 16, v236
	v_and_b32_e32 v3, 0xffff0000, v236
	v_lshlrev_b32_e32 v4, 16, v237
	v_and_b32_e32 v5, 0xffff0000, v237
	v_pk_mul_f32 v[2:3], v[2:3], v[12:13] op_sel_hi:[1,0]
	v_pk_mul_f32 v[4:5], v[4:5], v[12:13] op_sel_hi:[1,0]
	v_pk_mul_f32 v[2:3], v[2:3], v[60:61]
	v_pk_mul_f32 v[4:5], v[4:5], v[62:63]
	v_cvt_pk_bf16_f32 v232, v2, v3
	v_cvt_pk_bf16_f32 v233, v4, v5
	v_lshlrev_b32_e32 v2, 16, v238
	v_and_b32_e32 v3, 0xffff0000, v238
	v_lshlrev_b32_e32 v4, 16, v239
	v_and_b32_e32 v5, 0xffff0000, v239
	v_pk_mul_f32 v[2:3], v[2:3], v[12:13] op_sel_hi:[1,0]
	v_pk_mul_f32 v[4:5], v[4:5], v[12:13] op_sel_hi:[1,0]
	v_pk_mul_f32 v[2:3], v[2:3], v[98:99]
	v_pk_mul_f32 v[4:5], v[4:5], v[100:101]
	v_cvt_pk_bf16_f32 v234, v2, v3
	v_cvt_pk_bf16_f32 v235, v4, v5
	v_lshlrev_b32_e32 v2, 16, v240
	v_and_b32_e32 v3, 0xffff0000, v240
	v_lshlrev_b32_e32 v4, 16, v241
	v_and_b32_e32 v5, 0xffff0000, v241
	v_pk_mul_f32 v[2:3], v[2:3], v[12:13] op_sel_hi:[1,0]
	v_pk_mul_f32 v[4:5], v[4:5], v[12:13] op_sel_hi:[1,0]
	v_pk_mul_f32 v[2:3], v[2:3], v[102:103]
	v_pk_mul_f32 v[4:5], v[4:5], v[104:105]
	v_cvt_pk_bf16_f32 v236, v2, v3
	v_cvt_pk_bf16_f32 v237, v4, v5
	v_lshlrev_b32_e32 v2, 16, v242
	v_and_b32_e32 v3, 0xffff0000, v242
	v_lshlrev_b32_e32 v4, 16, v243
	v_and_b32_e32 v5, 0xffff0000, v243
	v_pk_mul_f32 v[2:3], v[2:3], v[12:13] op_sel_hi:[1,0]
	v_pk_mul_f32 v[4:5], v[4:5], v[12:13] op_sel_hi:[1,0]
	v_pk_mul_f32 v[2:3], v[2:3], v[106:107]
	v_pk_mul_f32 v[4:5], v[4:5], v[108:109]
	v_cvt_pk_bf16_f32 v238, v2, v3
	v_cvt_pk_bf16_f32 v239, v4, v5
	v_lshlrev_b32_e32 v2, 16, v244
	v_and_b32_e32 v3, 0xffff0000, v244
	v_lshlrev_b32_e32 v4, 16, v245
	v_and_b32_e32 v5, 0xffff0000, v245
	v_pk_mul_f32 v[2:3], v[2:3], v[12:13] op_sel_hi:[1,0]
	v_pk_mul_f32 v[4:5], v[4:5], v[12:13] op_sel_hi:[1,0]
	v_pk_mul_f32 v[2:3], v[2:3], v[110:111]
	v_pk_mul_f32 v[4:5], v[4:5], v[112:113]
	v_cvt_pk_bf16_f32 v240, v2, v3
	v_cvt_pk_bf16_f32 v241, v4, v5
	v_lshlrev_b32_e32 v2, 16, v246
	v_and_b32_e32 v3, 0xffff0000, v246
	v_lshlrev_b32_e32 v4, 16, v247
	v_and_b32_e32 v5, 0xffff0000, v247
	v_pk_mul_f32 v[2:3], v[2:3], v[12:13] op_sel_hi:[1,0]
	v_pk_mul_f32 v[4:5], v[4:5], v[12:13] op_sel_hi:[1,0]
	v_pk_mul_f32 v[2:3], v[2:3], v[114:115]
	v_pk_mul_f32 v[4:5], v[4:5], v[116:117]
	v_cvt_pk_bf16_f32 v242, v2, v3
	v_cvt_pk_bf16_f32 v243, v4, v5
	v_lshlrev_b32_e32 v2, 16, v248
	v_and_b32_e32 v3, 0xffff0000, v248
	v_lshlrev_b32_e32 v4, 16, v249
	v_and_b32_e32 v5, 0xffff0000, v249
	v_pk_mul_f32 v[2:3], v[2:3], v[12:13] op_sel_hi:[1,0]
	v_pk_mul_f32 v[4:5], v[4:5], v[12:13] op_sel_hi:[1,0]
	v_pk_mul_f32 v[2:3], v[2:3], v[118:119]
	v_pk_mul_f32 v[4:5], v[4:5], v[120:121]
	v_cvt_pk_bf16_f32 v244, v2, v3
	v_cvt_pk_bf16_f32 v245, v4, v5
	s_setprio 1
	v_cmp_lt_u32_e32 vcc, 255, v131
	s_nop 4
	s_cbranch_vccz .Lpeer_prio
	s_setprio 2
; __device__ void ph_peer(const float* __restrict__ SC, const bf16_t* __restrict__ H  , const float* __restrict__ gffn, const unsigned char* __restrict__ U, const unsigned char* __restrict__ V, float* X, const float* __restrict__ fgain) {
;     ...
;         float acc[32];
; #pragma unroll
;         for (int i = 0; i < 32; ++i) acc[i] = 0.f;
;         __builtin_amdgcn_s_setprio(1);
; #pragma unroll 1
;         for (int it = 0; it < 32; ++it) {
;             const int src = (it * 4 + grp) & 63;
;             const int e = __shfl(it < 16 ? idx_lo : idx_hi, src);
;             const float gt = __shfl(it < 16 ? g_lo : g_hi, src);
;             const u32x4* up = (const u32x4*)(U + (size_t)e * 768 + 48 * sub);
;             const u32x4 u0 = up[0], u1 = up[1], u2 = up[2];
.Lpeer_prio:
	v_mov_b32_e32 v126, 0
	s_mov_b32 s0, 0
	s_mov_b32 s1, 0
	v_mov_b32_e32 v127, v126
	v_mov_b32_e32 v144, v126
	v_mov_b32_e32 v145, v126
	v_mov_b32_e32 v122, v126
	v_mov_b32_e32 v123, v126
	v_mov_b32_e32 v124, v126
	v_mov_b32_e32 v125, v126
	v_mov_b32_e32 v114, v126
	v_mov_b32_e32 v115, v126
	v_mov_b32_e32 v118, v126
	v_mov_b32_e32 v119, v126
	v_mov_b32_e32 v116, v126
	v_mov_b32_e32 v117, v126
	v_mov_b32_e32 v120, v126
	v_mov_b32_e32 v121, v126
	v_mov_b32_e32 v106, v126
	v_mov_b32_e32 v107, v126
	v_mov_b32_e32 v110, v126
	v_mov_b32_e32 v111, v126
	v_mov_b32_e32 v108, v126
	v_mov_b32_e32 v109, v126
	v_mov_b32_e32 v112, v126
	v_mov_b32_e32 v113, v126
	v_mov_b32_e32 v98, v126
	v_mov_b32_e32 v99, v126
	v_mov_b32_e32 v102, v126
	v_mov_b32_e32 v103, v126
	v_mov_b32_e32 v100, v126
	v_mov_b32_e32 v101, v126
	v_mov_b32_e32 v104, v126
	v_mov_b32_e32 v105, v126
	s_movk_i32 s14, 0x300
	s_mov_b32 s16, 0x3e6d3388
	s_mov_b32 s24, 0x3f07dc22
	s_mov_b32 s28, 0x3f35f0e3
	s_mov_b32 s30, 0xbe11a98e
	s_mov_b32 s36, 0x3e027906
	s_barrier
	v_lshrrev_b32_e32 v61, 6, v131
	v_mul_u32_u24_e32 v61, 0x2400, v61
	v_lshl_add_u32 v61, v91, 2, v61
	s_mov_b32 s1, 0
	ds_read_b32 v56, v61
	v_add_u32_e32 v61, 16, v61
	s_add_i32 s1, s1, 1
	s_waitcnt lgkmcnt(0)
	v_mad_u32_u24 v0, v56, s14, v92
	global_load_dwordx4 v[32:35], v0, s[46:47]
	global_load_dwordx4 v[36:39], v0, s[46:47] offset:16
	global_load_dwordx4 v[40:43], v0, s[46:47] offset:32
